# hand-scheduled single-pass memory cross-attention core (8 key blocks, pipelined LDS reads, permlane row reductions)
# speedup vs baseline: 1.0472x; 1.0013x over previous
.LBB0_984:
	s_and_saveexec_b64 s[4:5], s[0:1]
	s_cbranch_execz .LBB0_952
	v_readlane_b32 s0, v254, 0
	v_readlane_b32 s1, v254, 1
	v_bfe_u32 v147, v6, 5, 1
	v_bfe_u32 v189, v6, 2, 2
	v_lshl_add_u64 v[144:145], v[0:1], 1, s[0:1]
	v_mul_u32_u24_e32 v188, 0x90, v7
	v_lshl_add_u32 v202, v147, 4, v188
	ds_read_b128 v[220:223], v202 offset:0
	ds_read_b128 v[224:227], v202 offset:32
	ds_read_b128 v[228:231], v202 offset:64
	ds_read_b128 v[232:235], v202 offset:96
	ds_read_b128 v[198:201], v202 offset:4608
	ds_read_b128 v[236:239], v202 offset:4640
	ds_read_b128 v[180:183], v202 offset:4672
	ds_read_b128 v[184:187], v202 offset:4704
	v_lshl_or_b32 v189, v147, 2, v189
	v_mul_u32_u24_e32 v205, 0xc0, v189
	v_lshlrev_b32_e32 v189, 1, v6
	v_and_b32_e32 v189, 32, v189
	v_lshlrev_b32_e32 v188, 3, v6
	v_and_b32_e32 v188, 24, v188
	v_add3_u32 v205, v205, v189, v188
	v_add_u32_e32 v205, 0x9000, v205
	v_lshlrev_b32_e32 v194, 3, v147
	v_xor_b32_e32 v218, 32, v197
	v_lshlrev_b32_e32 v218, 2, v218
	v_mov_b32_e32 v219, 0x3e38aa3b
	s_waitcnt vmcnt(0)
	s_waitcnt lgkmcnt(7)
	v_mfma_f32_32x32x16_bf16 v[16:31], v[220:223], v[116:119], 0
	s_waitcnt lgkmcnt(6)
	v_mfma_f32_32x32x16_bf16 v[16:31], v[224:227], v[120:123], v[16:31]
	s_waitcnt lgkmcnt(5)
	v_mfma_f32_32x32x16_bf16 v[16:31], v[228:231], v[124:127], v[16:31]
	s_waitcnt lgkmcnt(4)
	v_mfma_f32_32x32x16_bf16 v[16:31], v[232:235], v[128:131], v[16:31]
	ds_read_b128 v[220:223], v202 offset:9216
	ds_read_b128 v[224:227], v202 offset:9248
	ds_read_b128 v[228:231], v202 offset:9280
	ds_read_b128 v[232:235], v202 offset:9312
	s_waitcnt lgkmcnt(7)
	v_mfma_f32_32x32x16_bf16 v[32:47], v[198:201], v[116:119], 0
	s_waitcnt lgkmcnt(6)
	v_mfma_f32_32x32x16_bf16 v[32:47], v[236:239], v[120:123], v[32:47]
	s_waitcnt lgkmcnt(5)
	v_mfma_f32_32x32x16_bf16 v[32:47], v[180:183], v[124:127], v[32:47]
	s_waitcnt lgkmcnt(4)
	v_mfma_f32_32x32x16_bf16 v[32:47], v[184:187], v[128:131], v[32:47]
	ds_read_b128 v[198:201], v202 offset:13824
	ds_read_b128 v[236:239], v202 offset:13856
	ds_read_b128 v[180:183], v202 offset:13888
	ds_read_b128 v[184:187], v202 offset:13920
	s_waitcnt lgkmcnt(7)
	v_mfma_f32_32x32x16_bf16 v[48:63], v[220:223], v[116:119], 0
	s_waitcnt lgkmcnt(6)
	v_mfma_f32_32x32x16_bf16 v[48:63], v[224:227], v[120:123], v[48:63]
	s_waitcnt lgkmcnt(5)
	v_mfma_f32_32x32x16_bf16 v[48:63], v[228:231], v[124:127], v[48:63]
	s_waitcnt lgkmcnt(4)
	v_mfma_f32_32x32x16_bf16 v[48:63], v[232:235], v[128:131], v[48:63]
	ds_read_b128 v[220:223], v202 offset:18432
	ds_read_b128 v[224:227], v202 offset:18464
	ds_read_b128 v[228:231], v202 offset:18496
	ds_read_b128 v[232:235], v202 offset:18528
	s_waitcnt lgkmcnt(7)
	v_mfma_f32_32x32x16_bf16 v[64:79], v[198:201], v[116:119], 0
	s_waitcnt lgkmcnt(6)
	v_mfma_f32_32x32x16_bf16 v[64:79], v[236:239], v[120:123], v[64:79]
	s_waitcnt lgkmcnt(5)
	v_mfma_f32_32x32x16_bf16 v[64:79], v[180:183], v[124:127], v[64:79]
	s_waitcnt lgkmcnt(4)
	v_mfma_f32_32x32x16_bf16 v[64:79], v[184:187], v[128:131], v[64:79]
	ds_read_b128 v[198:201], v202 offset:23040
	ds_read_b128 v[236:239], v202 offset:23072
	ds_read_b128 v[180:183], v202 offset:23104
	ds_read_b128 v[184:187], v202 offset:23136
	s_waitcnt lgkmcnt(7)
	v_mfma_f32_32x32x16_bf16 v[80:95], v[220:223], v[116:119], 0
	s_waitcnt lgkmcnt(6)
	v_mfma_f32_32x32x16_bf16 v[80:95], v[224:227], v[120:123], v[80:95]
	s_waitcnt lgkmcnt(5)
	v_mfma_f32_32x32x16_bf16 v[80:95], v[228:231], v[124:127], v[80:95]
	s_waitcnt lgkmcnt(4)
	v_mfma_f32_32x32x16_bf16 v[80:95], v[232:235], v[128:131], v[80:95]
	ds_read_b128 v[220:223], v202 offset:27648
	ds_read_b128 v[224:227], v202 offset:27680
	ds_read_b128 v[228:231], v202 offset:27712
	ds_read_b128 v[232:235], v202 offset:27744
	s_waitcnt lgkmcnt(7)
	v_mfma_f32_32x32x16_bf16 v[148:163], v[198:201], v[116:119], 0
	s_waitcnt lgkmcnt(6)
	v_mfma_f32_32x32x16_bf16 v[148:163], v[236:239], v[120:123], v[148:163]
	s_waitcnt lgkmcnt(5)
	v_mfma_f32_32x32x16_bf16 v[148:163], v[180:183], v[124:127], v[148:163]
	s_waitcnt lgkmcnt(4)
	v_mfma_f32_32x32x16_bf16 v[148:163], v[184:187], v[128:131], v[148:163]
	ds_read_b128 v[198:201], v202 offset:32256
	ds_read_b128 v[236:239], v202 offset:32288
	ds_read_b128 v[180:183], v202 offset:32320
	ds_read_b128 v[184:187], v202 offset:32352
	s_waitcnt lgkmcnt(7)
	v_mfma_f32_32x32x16_bf16 v[164:179], v[220:223], v[116:119], 0
	s_waitcnt lgkmcnt(6)
	v_mfma_f32_32x32x16_bf16 v[164:179], v[224:227], v[120:123], v[164:179]
	s_waitcnt lgkmcnt(5)
	v_mfma_f32_32x32x16_bf16 v[164:179], v[228:231], v[124:127], v[164:179]
	s_waitcnt lgkmcnt(4)
	v_mfma_f32_32x32x16_bf16 v[164:179], v[232:235], v[128:131], v[164:179]
	s_waitcnt lgkmcnt(3)
	v_mfma_f32_32x32x16_bf16 v[0:15], v[198:201], v[116:119], 0
	s_waitcnt lgkmcnt(2)
	v_mfma_f32_32x32x16_bf16 v[0:15], v[236:239], v[120:123], v[0:15]
	s_waitcnt lgkmcnt(1)
	v_mfma_f32_32x32x16_bf16 v[0:15], v[180:183], v[124:127], v[0:15]
	s_waitcnt lgkmcnt(0)
	v_mfma_f32_32x32x16_bf16 v[0:15], v[184:187], v[128:131], v[0:15]
	v_max_f32_e32 v192, v16, v17
	v_max_f32_e32 v191, v18, v19
	v_max_f32_e32 v190, v20, v21
	v_max3_f32 v192, v192, v22, v23
	v_max3_f32 v191, v191, v24, v25
	v_max3_f32 v190, v190, v26, v27
	v_max3_f32 v192, v192, v28, v29
	v_max3_f32 v191, v191, v30, v31
	v_max3_f32 v190, v190, v32, v33
	v_max3_f32 v192, v192, v34, v35
	v_max3_f32 v191, v191, v36, v37
	v_max3_f32 v190, v190, v38, v39
	v_max3_f32 v192, v192, v40, v41
	v_max3_f32 v191, v191, v42, v43
	v_max3_f32 v190, v190, v44, v45
	v_max3_f32 v192, v192, v46, v47
	v_max3_f32 v191, v191, v48, v49
	v_max3_f32 v190, v190, v50, v51
	v_max3_f32 v192, v192, v52, v53
	v_max3_f32 v191, v191, v54, v55
	v_max3_f32 v190, v190, v56, v57
	v_max3_f32 v192, v192, v58, v59
	v_max3_f32 v191, v191, v60, v61
	v_max3_f32 v190, v190, v62, v63
	v_max3_f32 v192, v192, v64, v65
	v_max3_f32 v191, v191, v66, v67
	v_max3_f32 v190, v190, v68, v69
	v_max3_f32 v192, v192, v70, v71
	v_max3_f32 v191, v191, v72, v73
	v_max3_f32 v190, v190, v74, v75
	v_max3_f32 v192, v192, v76, v77
	v_max3_f32 v191, v191, v78, v79
	v_max3_f32 v190, v190, v80, v81
	v_max3_f32 v192, v192, v82, v83
	v_max3_f32 v191, v191, v84, v85
	v_max3_f32 v190, v190, v86, v87
	v_max3_f32 v192, v192, v88, v89
	v_max3_f32 v191, v191, v90, v91
	v_max3_f32 v190, v190, v92, v93
	v_max3_f32 v192, v192, v94, v95
	v_max3_f32 v191, v191, v148, v149
	v_max3_f32 v190, v190, v150, v151
	v_max3_f32 v192, v192, v152, v153
	v_max3_f32 v191, v191, v154, v155
	v_max3_f32 v190, v190, v156, v157
	v_max3_f32 v192, v192, v158, v159
	v_max3_f32 v191, v191, v160, v161
	v_max3_f32 v190, v190, v162, v163
	v_max3_f32 v192, v192, v164, v165
	v_max3_f32 v191, v191, v166, v167
	v_max3_f32 v190, v190, v168, v169
	v_max3_f32 v192, v192, v170, v171
	v_max3_f32 v191, v191, v172, v173
	v_max3_f32 v190, v190, v174, v175
	v_max3_f32 v192, v192, v176, v177
	v_max3_f32 v191, v191, v178, v179
	v_max3_f32 v190, v190, v0, v1
	v_max3_f32 v192, v192, v2, v3
	v_max3_f32 v191, v191, v4, v5
	v_max3_f32 v190, v190, v6, v7
	v_max3_f32 v192, v192, v8, v9
	v_max3_f32 v191, v191, v10, v11
	v_max3_f32 v190, v190, v12, v13
	v_max3_f32 v192, v192, v14, v15
	v_max3_f32 v192, v192, v191, v190
	v_mov_b32_e32 v191, v192
	s_nop 1
	v_permlane32_swap_b32_e32 v192, v191
	v_max_f32_e32 v192, v192, v191
	v_mul_f32_e32 v192, v219, v192
	ds_read_b64_tr_b16 v[198:199], v205
	ds_read_b64_tr_b16 v[200:201], v205 offset:1536
	ds_read_b64_tr_b16 v[236:237], v205 offset:64
	ds_read_b64_tr_b16 v[238:239], v205 offset:1600
	v_fma_f32 v0, v0, v219, -v192
	v_fma_f32 v1, v1, v219, -v192
	v_fma_f32 v2, v2, v219, -v192
	v_fma_f32 v3, v3, v219, -v192
	v_fma_f32 v4, v4, v219, -v192
	v_fma_f32 v5, v5, v219, -v192
	v_fma_f32 v6, v6, v219, -v192
	v_fma_f32 v7, v7, v219, -v192
	v_exp_f32_e32 v0, v0
	v_exp_f32_e32 v1, v1
	v_exp_f32_e32 v2, v2
	v_exp_f32_e32 v3, v3
	v_exp_f32_e32 v4, v4
	v_exp_f32_e32 v5, v5
	v_exp_f32_e32 v6, v6
	v_exp_f32_e32 v7, v7
	v_mov_b32_e32 v188, v0
	v_mov_b32_e32 v189, v1
	v_mov_b32_e32 v190, v2
	v_mov_b32_e32 v191, v3
	v_add_f32_e32 v188, v188, v4
	v_add_f32_e32 v189, v189, v5
	v_add_f32_e32 v190, v190, v6
	v_add_f32_e32 v191, v191, v7
	v_cvt_pk_bf16_f32 v180, v0, v1
	v_cvt_pk_bf16_f32 v181, v2, v3
	v_cvt_pk_bf16_f32 v182, v4, v5
	v_cvt_pk_bf16_f32 v183, v6, v7
	v_fma_f32 v8, v8, v219, -v192
	v_fma_f32 v9, v9, v219, -v192
	v_fma_f32 v10, v10, v219, -v192
	v_fma_f32 v11, v11, v219, -v192
	v_fma_f32 v12, v12, v219, -v192
	v_fma_f32 v13, v13, v219, -v192
	v_fma_f32 v14, v14, v219, -v192
	v_fma_f32 v15, v15, v219, -v192
	v_exp_f32_e32 v8, v8
	v_exp_f32_e32 v9, v9
	v_exp_f32_e32 v10, v10
	v_exp_f32_e32 v11, v11
	v_exp_f32_e32 v12, v12
	v_exp_f32_e32 v13, v13
	v_exp_f32_e32 v14, v14
	v_exp_f32_e32 v15, v15
	v_add_f32_e32 v188, v188, v8
	v_add_f32_e32 v189, v189, v9
	v_add_f32_e32 v190, v190, v10
	v_add_f32_e32 v191, v191, v11
	v_add_f32_e32 v188, v188, v12
	v_add_f32_e32 v189, v189, v13
	v_add_f32_e32 v190, v190, v14
	v_add_f32_e32 v191, v191, v15
	v_cvt_pk_bf16_f32 v184, v8, v9
	v_cvt_pk_bf16_f32 v185, v10, v11
	v_cvt_pk_bf16_f32 v186, v12, v13
	v_cvt_pk_bf16_f32 v187, v14, v15
	v_fma_f32 v16, v16, v219, -v192
	v_fma_f32 v17, v17, v219, -v192
	v_fma_f32 v18, v18, v219, -v192
	v_fma_f32 v19, v19, v219, -v192
	v_fma_f32 v20, v20, v219, -v192
	v_fma_f32 v21, v21, v219, -v192
	v_fma_f32 v22, v22, v219, -v192
	v_fma_f32 v23, v23, v219, -v192
	v_exp_f32_e32 v16, v16
	v_exp_f32_e32 v17, v17
	v_exp_f32_e32 v18, v18
	v_exp_f32_e32 v19, v19
	v_exp_f32_e32 v20, v20
	v_exp_f32_e32 v21, v21
	v_exp_f32_e32 v22, v22
	v_exp_f32_e32 v23, v23
	v_add_f32_e32 v188, v188, v16
	v_add_f32_e32 v189, v189, v17
	v_add_f32_e32 v190, v190, v18
	v_add_f32_e32 v191, v191, v19
	v_add_f32_e32 v188, v188, v20
	v_add_f32_e32 v189, v189, v21
	v_add_f32_e32 v190, v190, v22
	v_add_f32_e32 v191, v191, v23
	v_cvt_pk_bf16_f32 v16, v16, v17
	v_cvt_pk_bf16_f32 v17, v18, v19
	v_cvt_pk_bf16_f32 v18, v20, v21
	v_cvt_pk_bf16_f32 v19, v22, v23
	v_fma_f32 v24, v24, v219, -v192
	v_fma_f32 v25, v25, v219, -v192
	v_fma_f32 v26, v26, v219, -v192
	v_fma_f32 v27, v27, v219, -v192
	v_fma_f32 v28, v28, v219, -v192
	v_fma_f32 v29, v29, v219, -v192
	v_fma_f32 v30, v30, v219, -v192
	v_fma_f32 v31, v31, v219, -v192
	v_exp_f32_e32 v24, v24
	v_exp_f32_e32 v25, v25
	v_exp_f32_e32 v26, v26
	v_exp_f32_e32 v27, v27
	v_exp_f32_e32 v28, v28
	v_exp_f32_e32 v29, v29
	v_exp_f32_e32 v30, v30
	v_exp_f32_e32 v31, v31
	v_add_f32_e32 v188, v188, v24
	v_add_f32_e32 v189, v189, v25
	v_add_f32_e32 v190, v190, v26
	v_add_f32_e32 v191, v191, v27
	v_add_f32_e32 v188, v188, v28
	v_add_f32_e32 v189, v189, v29
	v_add_f32_e32 v190, v190, v30
	v_add_f32_e32 v191, v191, v31
	v_cvt_pk_bf16_f32 v20, v24, v25
	v_cvt_pk_bf16_f32 v21, v26, v27
	v_cvt_pk_bf16_f32 v22, v28, v29
	v_cvt_pk_bf16_f32 v23, v30, v31
	ds_read_b64_tr_b16 v[24:25], v205 offset:3072
	ds_read_b64_tr_b16 v[26:27], v205 offset:4608
	ds_read_b64_tr_b16 v[28:29], v205 offset:3136
	ds_read_b64_tr_b16 v[30:31], v205 offset:4672
	s_waitcnt lgkmcnt(6)
	v_mfma_f32_32x32x16_bf16 v[220:235], v[198:201], v[16:19], 0
	v_fma_f32 v32, v32, v219, -v192
	v_fma_f32 v33, v33, v219, -v192
	v_fma_f32 v34, v34, v219, -v192
	v_fma_f32 v35, v35, v219, -v192
	v_fma_f32 v36, v36, v219, -v192
	v_fma_f32 v37, v37, v219, -v192
	v_fma_f32 v38, v38, v219, -v192
	v_fma_f32 v39, v39, v219, -v192
	v_exp_f32_e32 v32, v32
	v_exp_f32_e32 v33, v33
	v_exp_f32_e32 v34, v34
	v_exp_f32_e32 v35, v35
	v_exp_f32_e32 v36, v36
	v_exp_f32_e32 v37, v37
	s_waitcnt lgkmcnt(4)
	v_mfma_f32_32x32x16_bf16 v[0:15], v[236:239], v[16:19], 0
	v_exp_f32_e32 v38, v38
	v_exp_f32_e32 v39, v39
	v_add_f32_e32 v188, v188, v32
	v_add_f32_e32 v189, v189, v33
	v_add_f32_e32 v190, v190, v34
	v_add_f32_e32 v191, v191, v35
	v_add_f32_e32 v188, v188, v36
	v_add_f32_e32 v189, v189, v37
	v_add_f32_e32 v190, v190, v38
	v_add_f32_e32 v191, v191, v39
	v_cvt_pk_bf16_f32 v32, v32, v33
	v_cvt_pk_bf16_f32 v33, v34, v35
	v_cvt_pk_bf16_f32 v34, v36, v37
	v_cvt_pk_bf16_f32 v35, v38, v39
	ds_read_b64_tr_b16 v[198:199], v205 offset:6144
	ds_read_b64_tr_b16 v[200:201], v205 offset:7680
	ds_read_b64_tr_b16 v[236:237], v205 offset:6208
	ds_read_b64_tr_b16 v[238:239], v205 offset:7744
	s_waitcnt lgkmcnt(6)
	v_mfma_f32_32x32x16_bf16 v[220:235], v[24:27], v[20:23], v[220:235]
	v_fma_f32 v40, v40, v219, -v192
	v_fma_f32 v41, v41, v219, -v192
	v_fma_f32 v42, v42, v219, -v192
	v_fma_f32 v43, v43, v219, -v192
	v_fma_f32 v44, v44, v219, -v192
	v_fma_f32 v45, v45, v219, -v192
	v_fma_f32 v46, v46, v219, -v192
	v_fma_f32 v47, v47, v219, -v192
	v_exp_f32_e32 v40, v40
	v_exp_f32_e32 v41, v41
	v_exp_f32_e32 v42, v42
	v_exp_f32_e32 v43, v43
	v_exp_f32_e32 v44, v44
	v_exp_f32_e32 v45, v45
	s_waitcnt lgkmcnt(4)
	v_mfma_f32_32x32x16_bf16 v[0:15], v[28:31], v[20:23], v[0:15]
	v_exp_f32_e32 v46, v46
	v_exp_f32_e32 v47, v47
	v_add_f32_e32 v188, v188, v40
	v_add_f32_e32 v189, v189, v41
	v_add_f32_e32 v190, v190, v42
	v_add_f32_e32 v191, v191, v43
	v_add_f32_e32 v188, v188, v44
	v_add_f32_e32 v189, v189, v45
	v_add_f32_e32 v190, v190, v46
	v_add_f32_e32 v191, v191, v47
	v_cvt_pk_bf16_f32 v36, v40, v41
	v_cvt_pk_bf16_f32 v37, v42, v43
	v_cvt_pk_bf16_f32 v38, v44, v45
	v_cvt_pk_bf16_f32 v39, v46, v47
	ds_read_b64_tr_b16 v[24:25], v205 offset:9216
	ds_read_b64_tr_b16 v[26:27], v205 offset:10752
	ds_read_b64_tr_b16 v[28:29], v205 offset:9280
	ds_read_b64_tr_b16 v[30:31], v205 offset:10816
	ds_read_b64_tr_b16 v[40:41], v205 offset:12288
	ds_read_b64_tr_b16 v[42:43], v205 offset:13824
	ds_read_b64_tr_b16 v[44:45], v205 offset:12352
	ds_read_b64_tr_b16 v[46:47], v205 offset:13888
	s_waitcnt lgkmcnt(10)
	v_mfma_f32_32x32x16_bf16 v[220:235], v[198:201], v[32:35], v[220:235]
	v_fma_f32 v48, v48, v219, -v192
	v_fma_f32 v49, v49, v219, -v192
	v_fma_f32 v50, v50, v219, -v192
	v_fma_f32 v51, v51, v219, -v192
	v_fma_f32 v52, v52, v219, -v192
	v_fma_f32 v53, v53, v219, -v192
	v_fma_f32 v54, v54, v219, -v192
	v_fma_f32 v55, v55, v219, -v192
	v_exp_f32_e32 v48, v48
	v_exp_f32_e32 v49, v49
	v_exp_f32_e32 v50, v50
	v_exp_f32_e32 v51, v51
	v_exp_f32_e32 v52, v52
	v_exp_f32_e32 v53, v53
	s_waitcnt lgkmcnt(8)
	v_mfma_f32_32x32x16_bf16 v[0:15], v[236:239], v[32:35], v[0:15]
	v_exp_f32_e32 v54, v54
	v_exp_f32_e32 v55, v55
	v_add_f32_e32 v188, v188, v48
	v_add_f32_e32 v189, v189, v49
	v_add_f32_e32 v190, v190, v50
	v_add_f32_e32 v191, v191, v51
	v_add_f32_e32 v188, v188, v52
	v_add_f32_e32 v189, v189, v53
	v_add_f32_e32 v190, v190, v54
	v_add_f32_e32 v191, v191, v55
	v_cvt_pk_bf16_f32 v48, v48, v49
	v_cvt_pk_bf16_f32 v49, v50, v51
	v_cvt_pk_bf16_f32 v50, v52, v53
	v_cvt_pk_bf16_f32 v51, v54, v55
	ds_read_b64_tr_b16 v[198:199], v205 offset:15360
	ds_read_b64_tr_b16 v[200:201], v205 offset:16896
	ds_read_b64_tr_b16 v[236:237], v205 offset:15424
	ds_read_b64_tr_b16 v[238:239], v205 offset:16960
	s_waitcnt lgkmcnt(10)
	v_mfma_f32_32x32x16_bf16 v[220:235], v[24:27], v[36:39], v[220:235]
	v_fma_f32 v56, v56, v219, -v192
	v_fma_f32 v57, v57, v219, -v192
	v_fma_f32 v58, v58, v219, -v192
	v_fma_f32 v59, v59, v219, -v192
	v_fma_f32 v60, v60, v219, -v192
	v_fma_f32 v61, v61, v219, -v192
	v_fma_f32 v62, v62, v219, -v192
	v_fma_f32 v63, v63, v219, -v192
	v_exp_f32_e32 v56, v56
	v_exp_f32_e32 v57, v57
	v_exp_f32_e32 v58, v58
	v_exp_f32_e32 v59, v59
	v_exp_f32_e32 v60, v60
	v_exp_f32_e32 v61, v61
	s_waitcnt lgkmcnt(8)
	v_mfma_f32_32x32x16_bf16 v[0:15], v[28:31], v[36:39], v[0:15]
	v_exp_f32_e32 v62, v62
	v_exp_f32_e32 v63, v63
	v_add_f32_e32 v188, v188, v56
	v_add_f32_e32 v189, v189, v57
	v_add_f32_e32 v190, v190, v58
	v_add_f32_e32 v191, v191, v59
	v_add_f32_e32 v188, v188, v60
	v_add_f32_e32 v189, v189, v61
	v_add_f32_e32 v190, v190, v62
	v_add_f32_e32 v191, v191, v63
	v_cvt_pk_bf16_f32 v52, v56, v57
	v_cvt_pk_bf16_f32 v53, v58, v59
	v_cvt_pk_bf16_f32 v54, v60, v61
	v_cvt_pk_bf16_f32 v55, v62, v63
	ds_read_b64_tr_b16 v[24:25], v205 offset:18432
	ds_read_b64_tr_b16 v[26:27], v205 offset:19968
	ds_read_b64_tr_b16 v[28:29], v205 offset:18496
	ds_read_b64_tr_b16 v[30:31], v205 offset:20032
	s_waitcnt lgkmcnt(10)
	v_mfma_f32_32x32x16_bf16 v[220:235], v[40:43], v[48:51], v[220:235]
	v_fma_f32 v64, v64, v219, -v192
	v_fma_f32 v65, v65, v219, -v192
	v_fma_f32 v66, v66, v219, -v192
	v_fma_f32 v67, v67, v219, -v192
	v_fma_f32 v68, v68, v219, -v192
	v_fma_f32 v69, v69, v219, -v192
	v_fma_f32 v70, v70, v219, -v192
	v_fma_f32 v71, v71, v219, -v192
	v_exp_f32_e32 v64, v64
	v_exp_f32_e32 v65, v65
	v_exp_f32_e32 v66, v66
	v_exp_f32_e32 v67, v67
	v_exp_f32_e32 v68, v68
	v_exp_f32_e32 v69, v69
	s_waitcnt lgkmcnt(8)
	v_mfma_f32_32x32x16_bf16 v[0:15], v[44:47], v[48:51], v[0:15]
	v_exp_f32_e32 v70, v70
	v_exp_f32_e32 v71, v71
	v_add_f32_e32 v188, v188, v64
	v_add_f32_e32 v189, v189, v65
	v_add_f32_e32 v190, v190, v66
	v_add_f32_e32 v191, v191, v67
	v_add_f32_e32 v188, v188, v68
	v_add_f32_e32 v189, v189, v69
	v_add_f32_e32 v190, v190, v70
	v_add_f32_e32 v191, v191, v71
	v_cvt_pk_bf16_f32 v64, v64, v65
	v_cvt_pk_bf16_f32 v65, v66, v67
	v_cvt_pk_bf16_f32 v66, v68, v69
	v_cvt_pk_bf16_f32 v67, v70, v71
	ds_read_b64_tr_b16 v[40:41], v205 offset:21504
	ds_read_b64_tr_b16 v[42:43], v205 offset:23040
	ds_read_b64_tr_b16 v[44:45], v205 offset:21568
	ds_read_b64_tr_b16 v[46:47], v205 offset:23104
	s_waitcnt lgkmcnt(10)
	v_mfma_f32_32x32x16_bf16 v[220:235], v[198:201], v[52:55], v[220:235]
	v_fma_f32 v72, v72, v219, -v192
	v_fma_f32 v73, v73, v219, -v192
	v_fma_f32 v74, v74, v219, -v192
	v_fma_f32 v75, v75, v219, -v192
	v_fma_f32 v76, v76, v219, -v192
	v_fma_f32 v77, v77, v219, -v192
	v_fma_f32 v78, v78, v219, -v192
	v_fma_f32 v79, v79, v219, -v192
	v_exp_f32_e32 v72, v72
	v_exp_f32_e32 v73, v73
	v_exp_f32_e32 v74, v74
	v_exp_f32_e32 v75, v75
	v_exp_f32_e32 v76, v76
	v_exp_f32_e32 v77, v77
	s_waitcnt lgkmcnt(8)
	v_mfma_f32_32x32x16_bf16 v[0:15], v[236:239], v[52:55], v[0:15]
	v_exp_f32_e32 v78, v78
	v_exp_f32_e32 v79, v79
	v_add_f32_e32 v188, v188, v72
	v_add_f32_e32 v189, v189, v73
	v_add_f32_e32 v190, v190, v74
	v_add_f32_e32 v191, v191, v75
	v_add_f32_e32 v188, v188, v76
	v_add_f32_e32 v189, v189, v77
	v_add_f32_e32 v190, v190, v78
	v_add_f32_e32 v191, v191, v79
	v_cvt_pk_bf16_f32 v68, v72, v73
	v_cvt_pk_bf16_f32 v69, v74, v75
	v_cvt_pk_bf16_f32 v70, v76, v77
	v_cvt_pk_bf16_f32 v71, v78, v79
	ds_read_b64_tr_b16 v[198:199], v205 offset:24576
	ds_read_b64_tr_b16 v[200:201], v205 offset:26112
	ds_read_b64_tr_b16 v[236:237], v205 offset:24640
	ds_read_b64_tr_b16 v[238:239], v205 offset:26176
	s_waitcnt lgkmcnt(10)
	v_mfma_f32_32x32x16_bf16 v[220:235], v[24:27], v[64:67], v[220:235]
	v_fma_f32 v80, v80, v219, -v192
	v_fma_f32 v81, v81, v219, -v192
	v_fma_f32 v82, v82, v219, -v192
	v_fma_f32 v83, v83, v219, -v192
	v_fma_f32 v84, v84, v219, -v192
	v_fma_f32 v85, v85, v219, -v192
	v_fma_f32 v86, v86, v219, -v192
	v_fma_f32 v87, v87, v219, -v192
	v_exp_f32_e32 v80, v80
	v_exp_f32_e32 v81, v81
	v_exp_f32_e32 v82, v82
	v_exp_f32_e32 v83, v83
	v_exp_f32_e32 v84, v84
	v_exp_f32_e32 v85, v85
	s_waitcnt lgkmcnt(8)
	v_mfma_f32_32x32x16_bf16 v[0:15], v[28:31], v[64:67], v[0:15]
	v_exp_f32_e32 v86, v86
	v_exp_f32_e32 v87, v87
	v_add_f32_e32 v188, v188, v80
	v_add_f32_e32 v189, v189, v81
	v_add_f32_e32 v190, v190, v82
	v_add_f32_e32 v191, v191, v83
	v_add_f32_e32 v188, v188, v84
	v_add_f32_e32 v189, v189, v85
	v_add_f32_e32 v190, v190, v86
	v_add_f32_e32 v191, v191, v87
	v_cvt_pk_bf16_f32 v80, v80, v81
	v_cvt_pk_bf16_f32 v81, v82, v83
	v_cvt_pk_bf16_f32 v82, v84, v85
	v_cvt_pk_bf16_f32 v83, v86, v87
	ds_read_b64_tr_b16 v[24:25], v205 offset:27648
	ds_read_b64_tr_b16 v[26:27], v205 offset:29184
	ds_read_b64_tr_b16 v[28:29], v205 offset:27712
	ds_read_b64_tr_b16 v[30:31], v205 offset:29248
	s_waitcnt lgkmcnt(10)
	v_mfma_f32_32x32x16_bf16 v[220:235], v[40:43], v[68:71], v[220:235]
	v_fma_f32 v88, v88, v219, -v192
	v_fma_f32 v89, v89, v219, -v192
	v_fma_f32 v90, v90, v219, -v192
	v_fma_f32 v91, v91, v219, -v192
	v_fma_f32 v92, v92, v219, -v192
	v_fma_f32 v93, v93, v219, -v192
	v_fma_f32 v94, v94, v219, -v192
	v_fma_f32 v95, v95, v219, -v192
	v_exp_f32_e32 v88, v88
	v_exp_f32_e32 v89, v89
	v_exp_f32_e32 v90, v90
	v_exp_f32_e32 v91, v91
	v_exp_f32_e32 v92, v92
	v_exp_f32_e32 v93, v93
	s_waitcnt lgkmcnt(8)
	v_mfma_f32_32x32x16_bf16 v[0:15], v[44:47], v[68:71], v[0:15]
	v_exp_f32_e32 v94, v94
	v_exp_f32_e32 v95, v95
	v_add_f32_e32 v188, v188, v88
	v_add_f32_e32 v189, v189, v89
	v_add_f32_e32 v190, v190, v90
	v_add_f32_e32 v191, v191, v91
	v_add_f32_e32 v188, v188, v92
	v_add_f32_e32 v189, v189, v93
	v_add_f32_e32 v190, v190, v94
	v_add_f32_e32 v191, v191, v95
	v_cvt_pk_bf16_f32 v84, v88, v89
	v_cvt_pk_bf16_f32 v85, v90, v91
	v_cvt_pk_bf16_f32 v86, v92, v93
	v_cvt_pk_bf16_f32 v87, v94, v95
	ds_read_b64_tr_b16 v[40:41], v205 offset:30720
	ds_read_b64_tr_b16 v[42:43], v205 offset:32256
	ds_read_b64_tr_b16 v[44:45], v205 offset:30784
	ds_read_b64_tr_b16 v[46:47], v205 offset:32320
	s_waitcnt lgkmcnt(10)
	v_mfma_f32_32x32x16_bf16 v[220:235], v[198:201], v[80:83], v[220:235]
	v_fma_f32 v148, v148, v219, -v192
	v_fma_f32 v149, v149, v219, -v192
	v_fma_f32 v150, v150, v219, -v192
	v_fma_f32 v151, v151, v219, -v192
	v_fma_f32 v152, v152, v219, -v192
	v_fma_f32 v153, v153, v219, -v192
	v_fma_f32 v154, v154, v219, -v192
	v_fma_f32 v155, v155, v219, -v192
	v_exp_f32_e32 v148, v148
	v_exp_f32_e32 v149, v149
	v_exp_f32_e32 v150, v150
	v_exp_f32_e32 v151, v151
	v_exp_f32_e32 v152, v152
	v_exp_f32_e32 v153, v153
	s_waitcnt lgkmcnt(8)
	v_mfma_f32_32x32x16_bf16 v[0:15], v[236:239], v[80:83], v[0:15]
	v_exp_f32_e32 v154, v154
	v_exp_f32_e32 v155, v155
	v_add_f32_e32 v188, v188, v148
	v_add_f32_e32 v189, v189, v149
	v_add_f32_e32 v190, v190, v150
	v_add_f32_e32 v191, v191, v151
	v_add_f32_e32 v188, v188, v152
	v_add_f32_e32 v189, v189, v153
	v_add_f32_e32 v190, v190, v154
	v_add_f32_e32 v191, v191, v155
	v_cvt_pk_bf16_f32 v148, v148, v149
	v_cvt_pk_bf16_f32 v149, v150, v151
	v_cvt_pk_bf16_f32 v150, v152, v153
	v_cvt_pk_bf16_f32 v151, v154, v155
	ds_read_b64_tr_b16 v[198:199], v205 offset:33792
	ds_read_b64_tr_b16 v[200:201], v205 offset:35328
	ds_read_b64_tr_b16 v[236:237], v205 offset:33856
	ds_read_b64_tr_b16 v[238:239], v205 offset:35392
	s_waitcnt lgkmcnt(10)
	v_mfma_f32_32x32x16_bf16 v[220:235], v[24:27], v[84:87], v[220:235]
	v_fma_f32 v156, v156, v219, -v192
	v_fma_f32 v157, v157, v219, -v192
	v_fma_f32 v158, v158, v219, -v192
	v_fma_f32 v159, v159, v219, -v192
	v_fma_f32 v160, v160, v219, -v192
	v_fma_f32 v161, v161, v219, -v192
	v_fma_f32 v162, v162, v219, -v192
	v_fma_f32 v163, v163, v219, -v192
	v_exp_f32_e32 v156, v156
	v_exp_f32_e32 v157, v157
	v_exp_f32_e32 v158, v158
	v_exp_f32_e32 v159, v159
	v_exp_f32_e32 v160, v160
	v_exp_f32_e32 v161, v161
	s_waitcnt lgkmcnt(8)
	v_mfma_f32_32x32x16_bf16 v[0:15], v[28:31], v[84:87], v[0:15]
	v_exp_f32_e32 v162, v162
	v_exp_f32_e32 v163, v163
	v_add_f32_e32 v188, v188, v156
	v_add_f32_e32 v189, v189, v157
	v_add_f32_e32 v190, v190, v158
	v_add_f32_e32 v191, v191, v159
	v_add_f32_e32 v188, v188, v160
	v_add_f32_e32 v189, v189, v161
	v_add_f32_e32 v190, v190, v162
	v_add_f32_e32 v191, v191, v163
	v_cvt_pk_bf16_f32 v152, v156, v157
	v_cvt_pk_bf16_f32 v153, v158, v159
	v_cvt_pk_bf16_f32 v154, v160, v161
	v_cvt_pk_bf16_f32 v155, v162, v163
	ds_read_b64_tr_b16 v[24:25], v205 offset:36864
	ds_read_b64_tr_b16 v[26:27], v205 offset:38400
	ds_read_b64_tr_b16 v[28:29], v205 offset:36928
	ds_read_b64_tr_b16 v[30:31], v205 offset:38464
	s_waitcnt lgkmcnt(10)
	v_mfma_f32_32x32x16_bf16 v[220:235], v[40:43], v[148:151], v[220:235]
	v_fma_f32 v164, v164, v219, -v192
	v_fma_f32 v165, v165, v219, -v192
	v_fma_f32 v166, v166, v219, -v192
	v_fma_f32 v167, v167, v219, -v192
	v_fma_f32 v168, v168, v219, -v192
	v_fma_f32 v169, v169, v219, -v192
	v_fma_f32 v170, v170, v219, -v192
	v_fma_f32 v171, v171, v219, -v192
	v_exp_f32_e32 v164, v164
	v_exp_f32_e32 v165, v165
	v_exp_f32_e32 v166, v166
	v_exp_f32_e32 v167, v167
	v_exp_f32_e32 v168, v168
	v_exp_f32_e32 v169, v169
	s_waitcnt lgkmcnt(8)
	v_mfma_f32_32x32x16_bf16 v[0:15], v[44:47], v[148:151], v[0:15]
	v_exp_f32_e32 v170, v170
	v_exp_f32_e32 v171, v171
	v_add_f32_e32 v188, v188, v164
	v_add_f32_e32 v189, v189, v165
	v_add_f32_e32 v190, v190, v166
	v_add_f32_e32 v191, v191, v167
	v_add_f32_e32 v188, v188, v168
	v_add_f32_e32 v189, v189, v169
	v_add_f32_e32 v190, v190, v170
	v_add_f32_e32 v191, v191, v171
	v_cvt_pk_bf16_f32 v164, v164, v165
	v_cvt_pk_bf16_f32 v165, v166, v167
	v_cvt_pk_bf16_f32 v166, v168, v169
	v_cvt_pk_bf16_f32 v167, v170, v171
	ds_read_b64_tr_b16 v[40:41], v205 offset:39936
	ds_read_b64_tr_b16 v[42:43], v205 offset:41472
	ds_read_b64_tr_b16 v[44:45], v205 offset:40000
	ds_read_b64_tr_b16 v[46:47], v205 offset:41536
	s_waitcnt lgkmcnt(10)
	v_mfma_f32_32x32x16_bf16 v[220:235], v[198:201], v[152:155], v[220:235]
	v_fma_f32 v172, v172, v219, -v192
	v_fma_f32 v173, v173, v219, -v192
	v_fma_f32 v174, v174, v219, -v192
	v_fma_f32 v175, v175, v219, -v192
	v_fma_f32 v176, v176, v219, -v192
	v_fma_f32 v177, v177, v219, -v192
	v_fma_f32 v178, v178, v219, -v192
	v_fma_f32 v179, v179, v219, -v192
	v_exp_f32_e32 v172, v172
	v_exp_f32_e32 v173, v173
	v_exp_f32_e32 v174, v174
	v_exp_f32_e32 v175, v175
	v_exp_f32_e32 v176, v176
	v_exp_f32_e32 v177, v177
	s_waitcnt lgkmcnt(8)
	v_mfma_f32_32x32x16_bf16 v[0:15], v[236:239], v[152:155], v[0:15]
	v_exp_f32_e32 v178, v178
	v_exp_f32_e32 v179, v179
	v_add_f32_e32 v188, v188, v172
	v_add_f32_e32 v189, v189, v173
	v_add_f32_e32 v190, v190, v174
	v_add_f32_e32 v191, v191, v175
	v_add_f32_e32 v188, v188, v176
	v_add_f32_e32 v189, v189, v177
	v_add_f32_e32 v190, v190, v178
	v_add_f32_e32 v191, v191, v179
	v_cvt_pk_bf16_f32 v168, v172, v173
	v_cvt_pk_bf16_f32 v169, v174, v175
	v_cvt_pk_bf16_f32 v170, v176, v177
	v_cvt_pk_bf16_f32 v171, v178, v179
	ds_read_b64_tr_b16 v[198:199], v205 offset:43008
	ds_read_b64_tr_b16 v[200:201], v205 offset:44544
	ds_read_b64_tr_b16 v[236:237], v205 offset:43072
	ds_read_b64_tr_b16 v[238:239], v205 offset:44608
	s_waitcnt lgkmcnt(10)
	v_mfma_f32_32x32x16_bf16 v[220:235], v[24:27], v[164:167], v[220:235]
	s_waitcnt lgkmcnt(8)
	v_mfma_f32_32x32x16_bf16 v[0:15], v[28:31], v[164:167], v[0:15]
	ds_read_b64_tr_b16 v[24:25], v205 offset:46080
	ds_read_b64_tr_b16 v[26:27], v205 offset:47616
	ds_read_b64_tr_b16 v[28:29], v205 offset:46144
	ds_read_b64_tr_b16 v[30:31], v205 offset:47680
	s_waitcnt lgkmcnt(10)
	v_mfma_f32_32x32x16_bf16 v[220:235], v[40:43], v[168:171], v[220:235]
	s_waitcnt lgkmcnt(8)
	v_mfma_f32_32x32x16_bf16 v[0:15], v[44:47], v[168:171], v[0:15]
	s_waitcnt lgkmcnt(6)
	v_mfma_f32_32x32x16_bf16 v[220:235], v[198:201], v[180:183], v[220:235]
	s_waitcnt lgkmcnt(4)
	v_mfma_f32_32x32x16_bf16 v[0:15], v[236:239], v[180:183], v[0:15]
	s_waitcnt lgkmcnt(2)
	v_mfma_f32_32x32x16_bf16 v[220:235], v[24:27], v[184:187], v[220:235]
	s_waitcnt lgkmcnt(0)
	v_mfma_f32_32x32x16_bf16 v[0:15], v[28:31], v[184:187], v[0:15]
	v_add_f32_e32 v188, v188, v189
	v_add_f32_e32 v190, v190, v191
	v_add_f32_e32 v188, v188, v190
	v_mov_b32_e32 v189, v188
	s_nop 1
	v_permlane32_swap_b32_e32 v188, v189
	v_add_f32_e32 v32, v188, v189
	v_div_scale_f32 v33, s[0:1], v32, v32, 1.0
	v_rcp_f32_e32 v34, v33
	s_nop 0
	v_fma_f32 v35, -v33, v34, 1.0
	v_fmac_f32_e32 v34, v35, v34
	v_div_scale_f32 v35, vcc, 1.0, v32, 1.0
	v_mul_f32_e32 v36, v35, v34
	v_fma_f32 v37, -v33, v36, v35
	v_fmac_f32_e32 v36, v37, v34
	v_fma_f32 v33, -v33, v36, v35
	s_nop 3
	v_div_fmas_f32 v33, v33, v34, v36
	v_div_fixup_f32 v32, v33, v32, 1.0
	v_lshl_add_u64 v[34:35], v[144:145], 0, v[194:195]
	v_pk_mul_f32 v[220:221], v[220:221], v[32:33] op_sel_hi:[1,0]
	v_pk_mul_f32 v[222:223], v[222:223], v[32:33] op_sel_hi:[1,0]
	v_pk_mul_f32 v[0:1], v[0:1], v[32:33] op_sel_hi:[1,0]
	v_pk_mul_f32 v[2:3], v[2:3], v[32:33] op_sel_hi:[1,0]
	v_cvt_pk_bf16_f32 v220, v220, v221
	v_cvt_pk_bf16_f32 v221, v222, v223
	v_cvt_pk_bf16_f32 v0, v0, v1
	v_cvt_pk_bf16_f32 v1, v2, v3
	global_store_dwordx2 v[34:35], v[220:221], off
	global_store_dwordx2 v[34:35], v[0:1], off offset:64
	v_pk_mul_f32 v[224:225], v[224:225], v[32:33] op_sel_hi:[1,0]
	v_pk_mul_f32 v[226:227], v[226:227], v[32:33] op_sel_hi:[1,0]
	v_pk_mul_f32 v[4:5], v[4:5], v[32:33] op_sel_hi:[1,0]
	v_pk_mul_f32 v[6:7], v[6:7], v[32:33] op_sel_hi:[1,0]
	v_cvt_pk_bf16_f32 v224, v224, v225
	v_cvt_pk_bf16_f32 v225, v226, v227
	v_cvt_pk_bf16_f32 v4, v4, v5
	v_cvt_pk_bf16_f32 v5, v6, v7
	global_store_dwordx2 v[34:35], v[224:225], off offset:16
	global_store_dwordx2 v[34:35], v[4:5], off offset:80
	v_pk_mul_f32 v[228:229], v[228:229], v[32:33] op_sel_hi:[1,0]
	v_pk_mul_f32 v[230:231], v[230:231], v[32:33] op_sel_hi:[1,0]
	v_pk_mul_f32 v[8:9], v[8:9], v[32:33] op_sel_hi:[1,0]
	v_pk_mul_f32 v[10:11], v[10:11], v[32:33] op_sel_hi:[1,0]
	v_cvt_pk_bf16_f32 v228, v228, v229
	v_cvt_pk_bf16_f32 v229, v230, v231
	v_cvt_pk_bf16_f32 v8, v8, v9
	v_cvt_pk_bf16_f32 v9, v10, v11
	global_store_dwordx2 v[34:35], v[228:229], off offset:32
	global_store_dwordx2 v[34:35], v[8:9], off offset:96
	v_pk_mul_f32 v[232:233], v[232:233], v[32:33] op_sel_hi:[1,0]
	v_pk_mul_f32 v[234:235], v[234:235], v[32:33] op_sel_hi:[1,0]
	v_pk_mul_f32 v[12:13], v[12:13], v[32:33] op_sel_hi:[1,0]
	v_pk_mul_f32 v[14:15], v[14:15], v[32:33] op_sel_hi:[1,0]
	v_cvt_pk_bf16_f32 v232, v232, v233
	v_cvt_pk_bf16_f32 v233, v234, v235
	v_cvt_pk_bf16_f32 v12, v12, v13
	v_cvt_pk_bf16_f32 v13, v14, v15
	global_store_dwordx2 v[34:35], v[232:233], off offset:48
	global_store_dwordx2 v[34:35], v[12:13], off offset:112
	s_branch .LBB0_952
